# P3|P4 barrier: exactly one L2 write-back per XCC, issued early by the last-arriving scan workgroup of that XCC (per-XCC scan-arrival counter); the barrier leader skips its write-back when teams are XC
# speedup vs baseline: 1.0001x; 1.0001x over previous
; __device__ __forceinline__ unsigned xb_add(unsigned* p, unsigned v) { return __hip_atomic_fetch_add(p, v, __ATOMIC_RELAXED, __HIP_MEMORY_SCOPE_AGENT); }
; __device__ __forceinline__ void xcd_barrier(const XcdBarrier& b) {
;     asm volatile("s_waitcnt vmcnt(0)" ::: "memory");
;     __syncthreads();
;     if (threadIdx.x == 0) {
;         unsigned* bar = b.bar;
;         __builtin_amdgcn_s_waitcnt(0);
;         unsigned nloc = b.st[0], nx = b.st[1];
;         if (nloc == 0u) { xcd_barrier_complete(bar, b.x, nloc, nx); b.st[0] = nloc; b.st[1] = nx; }
;         const unsigned old = xb_add(&bar[XB_XSUB(b.x)], 1u);
;         asm volatile("buffer_inv sc1" ::: "memory");
;         const unsigned gen = old / nloc;
;         if (old + 1u == (gen + 1u) * nloc) {
;             __builtin_amdgcn_fence(__ATOMIC_RELEASE, "agent");
;             asm volatile("s_waitcnt vmcnt(0)" ::: "memory");
;             const unsigned og = xb_add(&bar[XB_TOP], 1u);
;             const unsigned tg = og / nx;
;             if (og + 1u == (tg + 1u) * nx) xb_add(&bar[XB_TOPGEN], 1u);
.LBB0_841:
	s_waitcnt vmcnt(0)
	s_barrier
	s_and_saveexec_b64 s[0:1], s[96:97]
	s_cbranch_execz .LBB0_889
	v_mov_b32_e32 v9, 0x22968
	ds_read_b32 v10, v9
	v_mov_b32_e32 v9, 0x22960
	ds_read_b32 v11, v9
	s_waitcnt lgkmcnt(0)
	v_readfirstlane_b32 s101, v10
	s_nop 3
	s_cmp_eq_u32 s101, 0
	s_cbranch_scc1 .Lwb4_skip
	s_cmpk_gt_u32 s2, 63
	s_cbranch_scc1 .Lwb4_skip
	s_lshl_b32 s3, s90, 7
	s_add_u32 s6, s60, s3
	s_addc_u32 s7, s61, 0
	s_add_u32 s6, s6, 0x2c400
	s_addc_u32 s7, s7, 0
	v_mov_b32_e32 v1, 0
	v_mov_b32_e32 v2, 1
	s_waitcnt vmcnt(0)
	global_atomic_add v2, v1, v2, s[6:7] sc0
	v_lshrrev_b32_e32 v11, 2, v11
	v_add_u32_e32 v11, -1, v11
	s_waitcnt vmcnt(0)
	v_cmp_ne_u32_e32 vcc, v2, v11
	s_cbranch_vccnz .Lwb4_skip
	buffer_wbl2 sc1
	s_waitcnt vmcnt(0)

; __device__ __forceinline__ unsigned xb_ld(unsigned* p)              { return __hip_atomic_load(p, __ATOMIC_RELAXED, __HIP_MEMORY_SCOPE_AGENT); }
; __device__ __forceinline__ unsigned xb_add(unsigned* p, unsigned v) { return __hip_atomic_fetch_add(p, v, __ATOMIC_RELAXED, __HIP_MEMORY_SCOPE_AGENT); }
; #define XB_SPIN(cond, bar) do { unsigned _sp = 0; while (cond) { __builtin_amdgcn_s_sleep(1); \
;     if ((++_sp & 255u) == 0u) { if (xb_ld(&(bar)[XB_TMO])) break; if (_sp > XB_SPIN_CAP) { atomicAdd(&(bar)[XB_TMO], 1u); break; } } } } while (0)
; __device__ __forceinline__ void xcd_barrier(const XcdBarrier& b) {
;     ...
;         const unsigned old = xb_add(&bar[XB_XSUB(b.x)], 1u);
;         asm volatile("buffer_inv sc1" ::: "memory");
;         const unsigned gen = old / nloc;
;         if (old + 1u == (gen + 1u) * nloc) {
;             __builtin_amdgcn_fence(__ATOMIC_RELEASE, "agent");
;             asm volatile("s_waitcnt vmcnt(0)" ::: "memory");
;             const unsigned og = xb_add(&bar[XB_TOP], 1u);
;             const unsigned tg = og / nx;
;             if (og + 1u == (tg + 1u) * nx) xb_add(&bar[XB_TOPGEN], 1u);
;             else XB_SPIN(xb_ld(&bar[XB_TOPGEN]) == tg, bar);
;             asm volatile("" ::: "memory");
;             xb_add(&bar[XB_XGEN(b.x)], 1u);
;             asm volatile("s_waitcnt vmcnt(0)" ::: "memory");
.LBB0_857:
	s_lshl_b32 s3, s90, 8
	s_add_u32 s6, s58, s3
	s_addc_u32 s7, s59, 0
	v_mov_b32_e32 v2, 0x1000
	v_mov_b32_e32 v4, 1
	global_atomic_add v4, v2, v4, s[6:7] offset:1024 sc0
	v_cvt_f32_u32_e32 v2, v3
	v_sub_u32_e32 v5, 0, v3
	buffer_inv sc1
	v_rcp_iflag_f32_e32 v2, v2
	s_nop 0
	v_mul_f32_e32 v2, 0x4f7ffffe, v2
	v_cvt_u32_f32_e32 v2, v2
	v_mul_lo_u32 v5, v5, v2
	v_mul_hi_u32 v5, v2, v5
	v_add_u32_e32 v2, v2, v5
	s_waitcnt vmcnt(0)
	v_mul_hi_u32 v2, v4, v2
	v_mul_lo_u32 v5, v2, v3
	v_sub_u32_e32 v5, v4, v5
	v_add_u32_e32 v6, 1, v2
	v_cmp_ge_u32_e32 vcc, v5, v3
	v_add_u32_e32 v4, 1, v4
	s_nop 0
	v_cndmask_b32_e32 v2, v2, v6, vcc
	v_sub_u32_e32 v6, v5, v3
	v_cndmask_b32_e32 v5, v5, v6, vcc
	v_add_u32_e32 v6, 1, v2
	v_cmp_ge_u32_e32 vcc, v5, v3
	s_nop 1
	v_cndmask_b32_e32 v2, v2, v6, vcc
	v_mul_lo_u32 v5, v3, v2
	v_add_u32_e32 v3, v5, v3
	v_cmp_ne_u32_e32 vcc, v4, v3
	s_waitcnt lgkmcnt(0)
	v_add_u32_e32 v5, 1, v2
	v_mul_lo_u32 v5, v5, v1
	v_mov_b32_e32 v6, 0x3000
	v_mov_b32_e32 v8, 0
	s_cbranch_vccnz .Lxb4_spin
	s_cmp_lg_u32 s101, 0
	s_cbranch_scc1 .Lwb4_lead
	buffer_wbl2 sc1
	s_waitcnt vmcnt(0)
.Lwb4_lead:
	v_mov_b32_e32 v7, 1
	global_atomic_add v6, v7, s[58:59] offset:1024
